# residual epilogue: 16 loads in flight + pipelined second half instead of serial load-wait-fma-store ladder
# baseline (speedup 1.0000x reference)
.LBB0_277:
	v_lshl_add_u32 v140, s42, 8, v142
	v_lshl_or_b32 v136, s43, 8, v144
	v_ashrrev_i32_e32 v141, 31, v140
	v_ashrrev_i32_e32 v137, 31, v136
	v_lshlrev_b64 v[138:139], 12, v[140:141]
	v_lshl_add_u64 v[162:163], s[92:93], 0, v[138:139]
	v_lshlrev_b64 v[138:139], 2, v[136:137]
	v_lshl_add_u64 v[136:137], v[162:163], 0, v[138:139]
	global_load_dwordx4 v[164:167], v[136:137], off
	global_load_dwordx4 v[168:171], v[136:137], off offset:64
	global_load_dwordx4 v[172:175], v[136:137], off offset:512
	global_load_dwordx4 v[176:179], v[136:137], off offset:576
	s_mov_b64 s[14:15], 0x10000
	v_lshl_add_u64 v[138:139], v[136:137], 0, s[14:15]
	global_load_dwordx4 v[180:183], v[138:139], off
	global_load_dwordx4 v[184:187], v[138:139], off offset:64
	global_load_dwordx4 v[188:191], v[138:139], off offset:512
	global_load_dwordx4 v[192:195], v[138:139], off offset:576
	s_mov_b64 s[14:15], 0x20000
	v_lshl_add_u64 v[140:141], v[136:137], 0, s[14:15]
	global_load_dwordx4 v[196:199], v[140:141], off
	global_load_dwordx4 v[200:203], v[140:141], off offset:64
	global_load_dwordx4 v[204:207], v[140:141], off offset:512
	global_load_dwordx4 v[208:211], v[140:141], off offset:576
	s_mov_b64 s[14:15], 0x30000
	v_lshl_add_u64 v[162:163], v[136:137], 0, s[14:15]
	global_load_dwordx4 v[232:235], v[162:163], off
	global_load_dwordx4 v[236:239], v[162:163], off offset:64
	global_load_dwordx4 v[240:243], v[162:163], off offset:512
	global_load_dwordx4 v[244:247], v[162:163], off offset:576
	s_mov_b64 s[14:15], 0x80000
	v_lshl_add_u64 v[220:221], v[136:137], 0, s[14:15]
	s_mov_b64 s[14:15], 0x90000
	v_lshl_add_u64 v[222:223], v[136:137], 0, s[14:15]
	s_mov_b64 s[14:15], 0xa0000
	v_lshl_add_u64 v[248:249], v[136:137], 0, s[14:15]
	s_mov_b64 s[14:15], 0xb0000
	v_lshl_add_u64 v[250:251], v[136:137], 0, s[14:15]
	s_waitcnt vmcnt(15)
	v_pk_fma_f32 v[128:129], v[128:129], 0.5, v[166:167] op_sel_hi:[1,0,1]
	v_pk_fma_f32 v[126:127], v[126:127], 0.5, v[164:165] op_sel_hi:[1,0,1]
	global_store_dwordx4 v[136:137], v[126:129], off
	global_load_dwordx4 v[164:167], v[220:221], off
	s_waitcnt vmcnt(16)
	v_pk_fma_f32 v[124:125], v[124:125], 0.5, v[170:171] op_sel_hi:[1,0,1]
	v_pk_fma_f32 v[122:123], v[122:123], 0.5, v[168:169] op_sel_hi:[1,0,1]
	global_store_dwordx4 v[136:137], v[122:125], off offset:64
	global_load_dwordx4 v[168:171], v[220:221], off offset:64
	s_waitcnt vmcnt(17)
	v_pk_fma_f32 v[120:121], v[120:121], 0.5, v[174:175] op_sel_hi:[1,0,1]
	v_pk_fma_f32 v[118:119], v[118:119], 0.5, v[172:173] op_sel_hi:[1,0,1]
	global_store_dwordx4 v[136:137], v[118:121], off offset:512
	global_load_dwordx4 v[172:175], v[220:221], off offset:512
	s_waitcnt vmcnt(18)
	v_pk_fma_f32 v[116:117], v[116:117], 0.5, v[178:179] op_sel_hi:[1,0,1]
	v_pk_fma_f32 v[114:115], v[114:115], 0.5, v[176:177] op_sel_hi:[1,0,1]
	global_store_dwordx4 v[136:137], v[114:117], off offset:576
	global_load_dwordx4 v[176:179], v[220:221], off offset:576
	s_waitcnt vmcnt(19)
	v_pk_fma_f32 v[112:113], v[112:113], 0.5, v[182:183] op_sel_hi:[1,0,1]
	v_pk_fma_f32 v[110:111], v[110:111], 0.5, v[180:181] op_sel_hi:[1,0,1]
	global_store_dwordx4 v[138:139], v[110:113], off
	global_load_dwordx4 v[180:183], v[222:223], off
	s_waitcnt vmcnt(20)
	v_pk_fma_f32 v[108:109], v[108:109], 0.5, v[186:187] op_sel_hi:[1,0,1]
	v_pk_fma_f32 v[106:107], v[106:107], 0.5, v[184:185] op_sel_hi:[1,0,1]
	global_store_dwordx4 v[138:139], v[106:109], off offset:64
	global_load_dwordx4 v[184:187], v[222:223], off offset:64
	s_waitcnt vmcnt(21)
	v_pk_fma_f32 v[104:105], v[104:105], 0.5, v[190:191] op_sel_hi:[1,0,1]
	v_pk_fma_f32 v[102:103], v[102:103], 0.5, v[188:189] op_sel_hi:[1,0,1]
	global_store_dwordx4 v[138:139], v[102:105], off offset:512
	global_load_dwordx4 v[188:191], v[222:223], off offset:512
	s_waitcnt vmcnt(22)
	v_pk_fma_f32 v[100:101], v[100:101], 0.5, v[194:195] op_sel_hi:[1,0,1]
	v_pk_fma_f32 v[98:99], v[98:99], 0.5, v[192:193] op_sel_hi:[1,0,1]
	global_store_dwordx4 v[138:139], v[98:101], off offset:576
	global_load_dwordx4 v[192:195], v[222:223], off offset:576
	s_waitcnt vmcnt(23)
	v_pk_fma_f32 v[96:97], v[96:97], 0.5, v[198:199] op_sel_hi:[1,0,1]
	v_pk_fma_f32 v[94:95], v[94:95], 0.5, v[196:197] op_sel_hi:[1,0,1]
	global_store_dwordx4 v[140:141], v[94:97], off
	global_load_dwordx4 v[196:199], v[248:249], off
	s_waitcnt vmcnt(24)
	v_pk_fma_f32 v[92:93], v[92:93], 0.5, v[202:203] op_sel_hi:[1,0,1]
	v_pk_fma_f32 v[90:91], v[90:91], 0.5, v[200:201] op_sel_hi:[1,0,1]
	global_store_dwordx4 v[140:141], v[90:93], off offset:64
	global_load_dwordx4 v[200:203], v[248:249], off offset:64
	s_waitcnt vmcnt(25)
	v_pk_fma_f32 v[88:89], v[88:89], 0.5, v[206:207] op_sel_hi:[1,0,1]
	v_pk_fma_f32 v[86:87], v[86:87], 0.5, v[204:205] op_sel_hi:[1,0,1]
	global_store_dwordx4 v[140:141], v[86:89], off offset:512
	global_load_dwordx4 v[204:207], v[248:249], off offset:512
	s_waitcnt vmcnt(26)
	v_pk_fma_f32 v[84:85], v[84:85], 0.5, v[210:211] op_sel_hi:[1,0,1]
	v_pk_fma_f32 v[82:83], v[82:83], 0.5, v[208:209] op_sel_hi:[1,0,1]
	global_store_dwordx4 v[140:141], v[82:85], off offset:576
	global_load_dwordx4 v[208:211], v[248:249], off offset:576
	s_waitcnt vmcnt(27)
	v_pk_fma_f32 v[80:81], v[80:81], 0.5, v[234:235] op_sel_hi:[1,0,1]
	v_pk_fma_f32 v[78:79], v[78:79], 0.5, v[232:233] op_sel_hi:[1,0,1]
	global_store_dwordx4 v[162:163], v[78:81], off
	global_load_dwordx4 v[232:235], v[250:251], off
	s_waitcnt vmcnt(28)
	v_pk_fma_f32 v[76:77], v[76:77], 0.5, v[238:239] op_sel_hi:[1,0,1]
	v_pk_fma_f32 v[74:75], v[74:75], 0.5, v[236:237] op_sel_hi:[1,0,1]
	global_store_dwordx4 v[162:163], v[74:77], off offset:64
	global_load_dwordx4 v[236:239], v[250:251], off offset:64
	s_waitcnt vmcnt(29)
	v_pk_fma_f32 v[72:73], v[72:73], 0.5, v[242:243] op_sel_hi:[1,0,1]
	v_pk_fma_f32 v[70:71], v[70:71], 0.5, v[240:241] op_sel_hi:[1,0,1]
	global_store_dwordx4 v[162:163], v[70:73], off offset:512
	global_load_dwordx4 v[240:243], v[250:251], off offset:512
	s_waitcnt vmcnt(30)
	v_pk_fma_f32 v[68:69], v[68:69], 0.5, v[246:247] op_sel_hi:[1,0,1]
	v_pk_fma_f32 v[66:67], v[66:67], 0.5, v[244:245] op_sel_hi:[1,0,1]
	global_store_dwordx4 v[162:163], v[66:69], off offset:576
	global_load_dwordx4 v[244:247], v[250:251], off offset:576
	s_waitcnt vmcnt(30)
	v_pk_fma_f32 v[64:65], v[64:65], 0.5, v[166:167] op_sel_hi:[1,0,1]
	v_pk_fma_f32 v[62:63], v[62:63], 0.5, v[164:165] op_sel_hi:[1,0,1]
	global_store_dwordx4 v[220:221], v[62:65], off
	s_waitcnt vmcnt(29)
	v_pk_fma_f32 v[60:61], v[60:61], 0.5, v[170:171] op_sel_hi:[1,0,1]
	v_pk_fma_f32 v[58:59], v[58:59], 0.5, v[168:169] op_sel_hi:[1,0,1]
	global_store_dwordx4 v[220:221], v[58:61], off offset:64
	s_waitcnt vmcnt(28)
	v_pk_fma_f32 v[56:57], v[56:57], 0.5, v[174:175] op_sel_hi:[1,0,1]
	v_pk_fma_f32 v[54:55], v[54:55], 0.5, v[172:173] op_sel_hi:[1,0,1]
	global_store_dwordx4 v[220:221], v[54:57], off offset:512
	s_waitcnt vmcnt(27)
	v_pk_fma_f32 v[52:53], v[52:53], 0.5, v[178:179] op_sel_hi:[1,0,1]
	v_pk_fma_f32 v[50:51], v[50:51], 0.5, v[176:177] op_sel_hi:[1,0,1]
	global_store_dwordx4 v[220:221], v[50:53], off offset:576
	s_waitcnt vmcnt(26)
	v_pk_fma_f32 v[48:49], v[48:49], 0.5, v[182:183] op_sel_hi:[1,0,1]
	v_pk_fma_f32 v[46:47], v[46:47], 0.5, v[180:181] op_sel_hi:[1,0,1]
	global_store_dwordx4 v[222:223], v[46:49], off
	s_waitcnt vmcnt(25)
	v_pk_fma_f32 v[44:45], v[44:45], 0.5, v[186:187] op_sel_hi:[1,0,1]
	v_pk_fma_f32 v[42:43], v[42:43], 0.5, v[184:185] op_sel_hi:[1,0,1]
	global_store_dwordx4 v[222:223], v[42:45], off offset:64
	s_waitcnt vmcnt(24)
	v_pk_fma_f32 v[40:41], v[40:41], 0.5, v[190:191] op_sel_hi:[1,0,1]
	v_pk_fma_f32 v[38:39], v[38:39], 0.5, v[188:189] op_sel_hi:[1,0,1]
	global_store_dwordx4 v[222:223], v[38:41], off offset:512
	s_waitcnt vmcnt(23)
	v_pk_fma_f32 v[36:37], v[36:37], 0.5, v[194:195] op_sel_hi:[1,0,1]
	v_pk_fma_f32 v[34:35], v[34:35], 0.5, v[192:193] op_sel_hi:[1,0,1]
	global_store_dwordx4 v[222:223], v[34:37], off offset:576
	s_waitcnt vmcnt(22)
	v_pk_fma_f32 v[32:33], v[32:33], 0.5, v[198:199] op_sel_hi:[1,0,1]
	v_pk_fma_f32 v[30:31], v[30:31], 0.5, v[196:197] op_sel_hi:[1,0,1]
	global_store_dwordx4 v[248:249], v[30:33], off
	s_waitcnt vmcnt(21)
	v_pk_fma_f32 v[28:29], v[28:29], 0.5, v[202:203] op_sel_hi:[1,0,1]
	v_pk_fma_f32 v[26:27], v[26:27], 0.5, v[200:201] op_sel_hi:[1,0,1]
	global_store_dwordx4 v[248:249], v[26:29], off offset:64
	s_waitcnt vmcnt(20)
	v_pk_fma_f32 v[24:25], v[24:25], 0.5, v[206:207] op_sel_hi:[1,0,1]
	v_pk_fma_f32 v[22:23], v[22:23], 0.5, v[204:205] op_sel_hi:[1,0,1]
	global_store_dwordx4 v[248:249], v[22:25], off offset:512
	s_waitcnt vmcnt(19)
	v_pk_fma_f32 v[20:21], v[20:21], 0.5, v[210:211] op_sel_hi:[1,0,1]
	v_pk_fma_f32 v[18:19], v[18:19], 0.5, v[208:209] op_sel_hi:[1,0,1]
	global_store_dwordx4 v[248:249], v[18:21], off offset:576
	s_waitcnt vmcnt(18)
	v_pk_fma_f32 v[16:17], v[16:17], 0.5, v[234:235] op_sel_hi:[1,0,1]
	v_pk_fma_f32 v[14:15], v[14:15], 0.5, v[232:233] op_sel_hi:[1,0,1]
	global_store_dwordx4 v[250:251], v[14:17], off
	s_waitcnt vmcnt(17)
	v_pk_fma_f32 v[12:13], v[12:13], 0.5, v[238:239] op_sel_hi:[1,0,1]
	v_pk_fma_f32 v[10:11], v[10:11], 0.5, v[236:237] op_sel_hi:[1,0,1]
	global_store_dwordx4 v[250:251], v[10:13], off offset:64
	s_waitcnt vmcnt(16)
	v_pk_fma_f32 v[8:9], v[8:9], 0.5, v[242:243] op_sel_hi:[1,0,1]
	v_pk_fma_f32 v[6:7], v[6:7], 0.5, v[240:241] op_sel_hi:[1,0,1]
	global_store_dwordx4 v[250:251], v[6:9], off offset:512
	s_waitcnt vmcnt(15)
	v_pk_fma_f32 v[4:5], v[4:5], 0.5, v[246:247] op_sel_hi:[1,0,1]
	v_pk_fma_f32 v[2:3], v[2:3], 0.5, v[244:245] op_sel_hi:[1,0,1]
	global_store_dwordx4 v[250:251], v[2:5], off offset:576
	s_and_b64 vcc, exec, s[4:5]
	s_mov_b64 s[14:15], -1
	s_cbranch_vccnz .LBB0_262
	s_andn2_b64 vcc, exec, s[8:9]
	s_cbranch_vccnz .LBB0_261
	s_barrier
	s_branch .LBB0_261

.LBB0_1220:
	v_lshl_add_u32 v140, s18, 8, v142
	v_lshl_or_b32 v136, s19, 8, v144
	v_ashrrev_i32_e32 v141, 31, v140
	v_ashrrev_i32_e32 v137, 31, v136
	v_lshlrev_b64 v[138:139], 12, v[140:141]
	v_lshl_add_u64 v[162:163], s[92:93], 0, v[138:139]
	v_lshlrev_b64 v[138:139], 2, v[136:137]
	v_lshl_add_u64 v[136:137], v[162:163], 0, v[138:139]
	global_load_dwordx4 v[164:167], v[136:137], off
	global_load_dwordx4 v[168:171], v[136:137], off offset:64
	global_load_dwordx4 v[172:175], v[136:137], off offset:512
	global_load_dwordx4 v[176:179], v[136:137], off offset:576
	s_mov_b64 s[18:19], 0x10000
	v_lshl_add_u64 v[138:139], v[136:137], 0, s[18:19]
	global_load_dwordx4 v[180:183], v[138:139], off
	global_load_dwordx4 v[184:187], v[138:139], off offset:64
	global_load_dwordx4 v[188:191], v[138:139], off offset:512
	global_load_dwordx4 v[192:195], v[138:139], off offset:576
	s_mov_b64 s[18:19], 0x20000
	v_lshl_add_u64 v[140:141], v[136:137], 0, s[18:19]
	global_load_dwordx4 v[196:199], v[140:141], off
	global_load_dwordx4 v[200:203], v[140:141], off offset:64
	global_load_dwordx4 v[204:207], v[140:141], off offset:512
	global_load_dwordx4 v[208:211], v[140:141], off offset:576
	s_mov_b64 s[18:19], 0x30000
	v_lshl_add_u64 v[162:163], v[136:137], 0, s[18:19]
	global_load_dwordx4 v[232:235], v[162:163], off
	global_load_dwordx4 v[236:239], v[162:163], off offset:64
	global_load_dwordx4 v[240:243], v[162:163], off offset:512
	global_load_dwordx4 v[244:247], v[162:163], off offset:576
	s_mov_b64 s[18:19], 0x80000
	v_lshl_add_u64 v[220:221], v[136:137], 0, s[18:19]
	s_mov_b64 s[18:19], 0x90000
	v_lshl_add_u64 v[222:223], v[136:137], 0, s[18:19]
	s_mov_b64 s[18:19], 0xa0000
	v_lshl_add_u64 v[248:249], v[136:137], 0, s[18:19]
	s_mov_b64 s[18:19], 0xb0000
	v_lshl_add_u64 v[250:251], v[136:137], 0, s[18:19]
	s_waitcnt vmcnt(15)
	v_pk_add_f32 v[128:129], v[128:129], v[166:167]
	v_pk_add_f32 v[126:127], v[126:127], v[164:165]
	global_store_dwordx4 v[136:137], v[126:129], off
	global_load_dwordx4 v[164:167], v[220:221], off
	s_waitcnt vmcnt(16)
	v_pk_add_f32 v[124:125], v[124:125], v[170:171]
	v_pk_add_f32 v[122:123], v[122:123], v[168:169]
	global_store_dwordx4 v[136:137], v[122:125], off offset:64
	global_load_dwordx4 v[168:171], v[220:221], off offset:64
	s_waitcnt vmcnt(17)
	v_pk_add_f32 v[120:121], v[120:121], v[174:175]
	v_pk_add_f32 v[118:119], v[118:119], v[172:173]
	global_store_dwordx4 v[136:137], v[118:121], off offset:512
	global_load_dwordx4 v[172:175], v[220:221], off offset:512
	s_waitcnt vmcnt(18)
	v_pk_add_f32 v[116:117], v[116:117], v[178:179]
	v_pk_add_f32 v[114:115], v[114:115], v[176:177]
	global_store_dwordx4 v[136:137], v[114:117], off offset:576
	global_load_dwordx4 v[176:179], v[220:221], off offset:576
	s_waitcnt vmcnt(19)
	v_pk_add_f32 v[112:113], v[112:113], v[182:183]
	v_pk_add_f32 v[110:111], v[110:111], v[180:181]
	global_store_dwordx4 v[138:139], v[110:113], off
	global_load_dwordx4 v[180:183], v[222:223], off
	s_waitcnt vmcnt(20)
	v_pk_add_f32 v[108:109], v[108:109], v[186:187]
	v_pk_add_f32 v[106:107], v[106:107], v[184:185]
	global_store_dwordx4 v[138:139], v[106:109], off offset:64
	global_load_dwordx4 v[184:187], v[222:223], off offset:64
	s_waitcnt vmcnt(21)
	v_pk_add_f32 v[104:105], v[104:105], v[190:191]
	v_pk_add_f32 v[102:103], v[102:103], v[188:189]
	global_store_dwordx4 v[138:139], v[102:105], off offset:512
	global_load_dwordx4 v[188:191], v[222:223], off offset:512
	s_waitcnt vmcnt(22)
	v_pk_add_f32 v[100:101], v[100:101], v[194:195]
	v_pk_add_f32 v[98:99], v[98:99], v[192:193]
	global_store_dwordx4 v[138:139], v[98:101], off offset:576
	global_load_dwordx4 v[192:195], v[222:223], off offset:576
	s_waitcnt vmcnt(23)
	v_pk_add_f32 v[96:97], v[96:97], v[198:199]
	v_pk_add_f32 v[94:95], v[94:95], v[196:197]
	global_store_dwordx4 v[140:141], v[94:97], off
	global_load_dwordx4 v[196:199], v[248:249], off
	s_waitcnt vmcnt(24)
	v_pk_add_f32 v[92:93], v[92:93], v[202:203]
	v_pk_add_f32 v[90:91], v[90:91], v[200:201]
	global_store_dwordx4 v[140:141], v[90:93], off offset:64
	global_load_dwordx4 v[200:203], v[248:249], off offset:64
	s_waitcnt vmcnt(25)
	v_pk_add_f32 v[88:89], v[88:89], v[206:207]
	v_pk_add_f32 v[86:87], v[86:87], v[204:205]
	global_store_dwordx4 v[140:141], v[86:89], off offset:512
	global_load_dwordx4 v[204:207], v[248:249], off offset:512
	s_waitcnt vmcnt(26)
	v_pk_add_f32 v[84:85], v[84:85], v[210:211]
	v_pk_add_f32 v[82:83], v[82:83], v[208:209]
	global_store_dwordx4 v[140:141], v[82:85], off offset:576
	global_load_dwordx4 v[208:211], v[248:249], off offset:576
	s_waitcnt vmcnt(27)
	v_pk_add_f32 v[80:81], v[80:81], v[234:235]
	v_pk_add_f32 v[78:79], v[78:79], v[232:233]
	global_store_dwordx4 v[162:163], v[78:81], off
	global_load_dwordx4 v[232:235], v[250:251], off
	s_waitcnt vmcnt(28)
	v_pk_add_f32 v[76:77], v[76:77], v[238:239]
	v_pk_add_f32 v[74:75], v[74:75], v[236:237]
	global_store_dwordx4 v[162:163], v[74:77], off offset:64
	global_load_dwordx4 v[236:239], v[250:251], off offset:64
	s_waitcnt vmcnt(29)
	v_pk_add_f32 v[72:73], v[72:73], v[242:243]
	v_pk_add_f32 v[70:71], v[70:71], v[240:241]
	global_store_dwordx4 v[162:163], v[70:73], off offset:512
	global_load_dwordx4 v[240:243], v[250:251], off offset:512
	s_waitcnt vmcnt(30)
	v_pk_add_f32 v[68:69], v[68:69], v[246:247]
	v_pk_add_f32 v[66:67], v[66:67], v[244:245]
	global_store_dwordx4 v[162:163], v[66:69], off offset:576
	global_load_dwordx4 v[244:247], v[250:251], off offset:576
	s_waitcnt vmcnt(30)
	v_pk_add_f32 v[64:65], v[64:65], v[166:167]
	v_pk_add_f32 v[62:63], v[62:63], v[164:165]
	global_store_dwordx4 v[220:221], v[62:65], off
	s_waitcnt vmcnt(29)
	v_pk_add_f32 v[60:61], v[60:61], v[170:171]
	v_pk_add_f32 v[58:59], v[58:59], v[168:169]
	global_store_dwordx4 v[220:221], v[58:61], off offset:64
	s_waitcnt vmcnt(28)
	v_pk_add_f32 v[56:57], v[56:57], v[174:175]
	v_pk_add_f32 v[54:55], v[54:55], v[172:173]
	global_store_dwordx4 v[220:221], v[54:57], off offset:512
	s_waitcnt vmcnt(27)
	v_pk_add_f32 v[52:53], v[52:53], v[178:179]
	v_pk_add_f32 v[50:51], v[50:51], v[176:177]
	global_store_dwordx4 v[220:221], v[50:53], off offset:576
	s_waitcnt vmcnt(26)
	v_pk_add_f32 v[48:49], v[48:49], v[182:183]
	v_pk_add_f32 v[46:47], v[46:47], v[180:181]
	global_store_dwordx4 v[222:223], v[46:49], off
	s_waitcnt vmcnt(25)
	v_pk_add_f32 v[44:45], v[44:45], v[186:187]
	v_pk_add_f32 v[42:43], v[42:43], v[184:185]
	global_store_dwordx4 v[222:223], v[42:45], off offset:64
	s_waitcnt vmcnt(24)
	v_pk_add_f32 v[40:41], v[40:41], v[190:191]
	v_pk_add_f32 v[38:39], v[38:39], v[188:189]
	global_store_dwordx4 v[222:223], v[38:41], off offset:512
	s_waitcnt vmcnt(23)
	v_pk_add_f32 v[36:37], v[36:37], v[194:195]
	v_pk_add_f32 v[34:35], v[34:35], v[192:193]
	global_store_dwordx4 v[222:223], v[34:37], off offset:576
	s_waitcnt vmcnt(22)
	v_pk_add_f32 v[32:33], v[32:33], v[198:199]
	v_pk_add_f32 v[30:31], v[30:31], v[196:197]
	global_store_dwordx4 v[248:249], v[30:33], off
	s_waitcnt vmcnt(21)
	v_pk_add_f32 v[28:29], v[28:29], v[202:203]
	v_pk_add_f32 v[26:27], v[26:27], v[200:201]
	global_store_dwordx4 v[248:249], v[26:29], off offset:64
	s_waitcnt vmcnt(20)
	v_pk_add_f32 v[24:25], v[24:25], v[206:207]
	v_pk_add_f32 v[22:23], v[22:23], v[204:205]
	global_store_dwordx4 v[248:249], v[22:25], off offset:512
	s_waitcnt vmcnt(19)
	v_pk_add_f32 v[20:21], v[20:21], v[210:211]
	v_pk_add_f32 v[18:19], v[18:19], v[208:209]
	global_store_dwordx4 v[248:249], v[18:21], off offset:576
	s_waitcnt vmcnt(18)
	v_pk_add_f32 v[16:17], v[16:17], v[234:235]
	v_pk_add_f32 v[14:15], v[14:15], v[232:233]
	global_store_dwordx4 v[250:251], v[14:17], off
	s_waitcnt vmcnt(17)
	v_pk_add_f32 v[12:13], v[12:13], v[238:239]
	v_pk_add_f32 v[10:11], v[10:11], v[236:237]
	global_store_dwordx4 v[250:251], v[10:13], off offset:64
	s_waitcnt vmcnt(16)
	v_pk_add_f32 v[8:9], v[8:9], v[242:243]
	v_pk_add_f32 v[6:7], v[6:7], v[240:241]
	global_store_dwordx4 v[250:251], v[6:9], off offset:512
	s_waitcnt vmcnt(15)
	v_pk_add_f32 v[4:5], v[4:5], v[246:247]
	v_pk_add_f32 v[2:3], v[2:3], v[244:245]
	global_store_dwordx4 v[250:251], v[2:5], off offset:576
	s_andn2_b64 vcc, exec, s[4:5]
	s_mov_b64 s[18:19], -1
	s_cbranch_vccnz .LBB0_1209
	s_andn2_b64 vcc, exec, s[6:7]
	s_cbranch_vccnz .LBB0_1208
	s_barrier
	s_branch .LBB0_1208
